# baseline (speedup 1.0000x reference)
.LBB0_1498:
	s_waitcnt vmcnt(0)
	v_mov_b32_e32 v0, v131
	s_mov_b32 s2, s73
	s_mov_b32 s3, s83
	s_lshl_b32 s3, s3, 3
	s_abs_i32 s6, s3
	v_cvt_f32_u32_e32 v1, s6
	s_sub_i32 s7, 0, s6
	v_ashrrev_i32_e32 v2, 6, v0
	v_lshl_add_u32 v2, s2, 3, v2
	v_rcp_iflag_f32_e32 v1, v1
	s_add_i32 s2, s3, 0x7fff
	s_xor_b32 s3, s2, s3
	s_abs_i32 s2, s2
	v_mul_f32_e32 v1, 0x4f7ffffe, v1
	v_cvt_u32_f32_e32 v1, v1
	s_ashr_i32 s3, s3, 31
	v_readfirstlane_b32 s8, v1
	s_mul_i32 s7, s7, s8
	s_mul_hi_u32 s7, s8, s7
	s_add_i32 s8, s8, s7
	s_mul_hi_u32 s7, s2, s8
	s_mul_i32 s8, s7, s6
	s_sub_i32 s2, s2, s8
	s_add_i32 s8, s7, 1
	s_sub_i32 s9, s2, s6
	s_cmp_ge_u32 s2, s6
	s_cselect_b32 s7, s8, s7
	s_cselect_b32 s2, s9, s2
	s_add_i32 s8, s7, 1
	s_cmp_ge_u32 s2, s6
	s_cselect_b32 s2, s8, s7
	s_xor_b32 s2, s2, s3
	s_sub_i32 s2, s2, s3
	s_add_i32 s2, s2, 3
	s_and_b32 s2, s2, -4
	v_mul_lo_u32 v64, s2, v2
	v_add_u32_e32 v1, s2, v64
	v_min_i32_e32 v67, 0x8000, v1
	v_cmp_lt_i32_e32 vcc, v64, v67
	s_and_saveexec_b64 s[2:3], vcc
	s_cbranch_execz .LBB0_1526
	v_readlane_b32 s42, v255, 20
	s_add_i32 s34, s42, 1
	s_mul_i32 s7, s34, 0x18000
	v_readlane_b32 s8, v255, 15
	s_mul_hi_i32 s6, s34, 0x18000
	v_readlane_b32 s9, v255, 16
	s_add_u32 s12, s8, s7
	s_addc_u32 s13, s9, s6
	s_cmp_lt_i32 s42, 3
	s_waitcnt lgkmcnt(0)
	s_cselect_b64 s[14:15], -1, 0
	s_add_u32 s22, s12, 0x1000
	s_addc_u32 s23, s13, 0
	s_add_u32 s38, s26, 0x3981000
	s_addc_u32 s39, s27, 0
	s_add_u32 s40, s26, 0x3c00000
	s_addc_u32 s41, s27, 0
	s_and_b64 s[36:37], s[10:11], exec
	s_load_dwordx2 s[6:7], s[0:1], 0x20
	s_load_dwordx2 s[8:9], s[0:1], 0x38
	s_load_dwordx2 s[18:19], s[0:1], 0x98
	s_cselect_b32 s37, s41, 0
	s_cselect_b32 s36, s40, 0
	s_lshl_b32 s40, s34, 10
	s_ashr_i32 s41, s40, 31
	s_lshl_b64 s[40:41], s[40:41], 2
	s_waitcnt lgkmcnt(0)
	s_add_u32 s6, s6, s40
	s_addc_u32 s7, s7, s41
	v_lshlrev_b32_e32 v1, 2, v0
	s_and_b64 s[40:41], s[14:15], exec
	v_and_b32_e32 v66, 0xfc, v1
	s_cselect_b32 s47, s17, 0
	s_cselect_b32 s46, s16, 0
	s_lshl_b32 s40, s42, 10
	v_lshlrev_b32_e32 v128, 2, v66
	s_ashr_i32 s41, s40, 31
	v_lshl_add_u64 v[70:71], s[6:7], 0, v[128:129]
	v_readlane_b32 s6, v255, 18
	s_lshl_b64 s[40:41], s[40:41], 2
	v_readlane_b32 s7, v255, 19
	s_add_u32 s8, s8, s40
	v_ashrrev_i32_e32 v65, 31, v64
	v_lshl_add_u64 v[2:3], s[6:7], 0, v[128:129]
	s_mov_b64 s[6:7], 0x5000
	s_addc_u32 s9, s9, s41
	v_lshl_add_u64 v[74:75], v[2:3], 0, s[6:7]
	v_lshlrev_b64 v[2:3], 12, v[64:65]
	v_and_b32_e32 v4, 63, v0
	v_readlane_b32 s43, v255, 21
	s_cmp_lg_u64 s[46:47], 0
	v_lshl_or_b32 v2, v4, 4, v2
	s_cselect_b64 s[42:43], -1, 0
	s_cmp_lg_u64 s[36:37], 0
	v_lshl_add_u64 v[0:1], s[24:25], 0, v[2:3]
	s_mov_b64 s[6:7], 0x1000
	s_cselect_b64 s[68:69], -1, 0
	s_cmp_lg_u64 s[24:25], 0
	v_lshl_add_u64 v[76:77], v[0:1], 0, s[6:7]
	v_lshlrev_b64 v[0:1], 11, v[64:65]
	v_mov_b32_e32 v86, 0
	s_movk_i32 s34, 0x2000
	s_mov_b64 s[40:41], 0
	s_cselect_b64 s[70:71], -1, 0
	v_lshl_add_u64 v[68:69], s[8:9], 0, v[128:129]
	v_lshl_add_u64 v[72:73], s[18:19], 0, v[128:129]
	v_lshlrev_b32_e32 v78, 3, v4
	v_mov_b32_e32 v79, v129
	v_lshl_add_u64 v[80:81], s[26:27], 0, v[0:1]
	v_lshl_add_u64 v[82:83], s[36:37], 0, v[0:1]
	v_lshl_add_u64 v[84:85], s[46:47], 0, v[0:1]
	v_mov_b32_e32 v65, -1
	v_mov_b32_e32 v87, v86
	v_mov_b32_e32 v106, v86
	v_mov_b32_e32 v107, v86
	v_mov_b32_e32 v104, v86
	v_mov_b32_e32 v105, v86
	v_mov_b32_e32 v110, v86
	v_mov_b32_e32 v111, v86
	v_mov_b32_e32 v108, v86
	v_mov_b32_e32 v109, v86
	v_mov_b32_e32 v114, v86
	v_mov_b32_e32 v115, v86
	v_mov_b32_e32 v112, v86
	v_mov_b32_e32 v113, v86
	v_mov_b32_e32 v116, v86
	v_mov_b32_e32 v117, v86
	s_mov_b32 s101, 0
	s_branch .LBB0_1501

.LBB0_1519:
	s_or_b64 exec, exec, s[24:25]
	v_lshl_add_u64 v[138:139], v[80:81], 0, v[78:79]
	s_mov_b32 s6, 0xec00000
	v_add_co_u32_e32 v138, vcc, s6, v138
	s_nop 1
	v_addc_co_u32_e32 v139, vcc, 0, v139, vcc
	s_cmp_eq_u32 s101, 0
	s_cbranch_scc0 .Leb_have
	global_load_dwordx4 v[60:63], v[76:77], off offset:-4096 nt
	global_load_dwordx4 v[56:59], v[76:77], off offset:-3072 nt
	global_load_dwordx4 v[52:55], v[76:77], off offset:-2048 nt
	global_load_dwordx4 v[48:51], v[76:77], off offset:-1024 nt
	global_load_dwordx4 v[44:47], v[76:77], off nt
	global_load_dwordx4 v[40:43], v[76:77], off offset:1024 nt
	global_load_dwordx4 v[36:39], v[76:77], off offset:2048 nt
	global_load_dwordx4 v[32:35], v[76:77], off offset:3072 nt
	global_load_dwordx2 v[140:141], v[138:139], off nt
	global_load_dwordx2 v[144:145], v[138:139], off offset:512 nt
	global_load_dwordx2 v[148:149], v[138:139], off offset:1024 nt
	global_load_dwordx2 v[152:153], v[138:139], off offset:1536 nt
	global_load_dwordx2 v[160:161], v[138:139], off offset:2048 nt
	global_load_dwordx2 v[166:167], v[138:139], off offset:2560 nt
	global_load_dwordx2 v[168:169], v[138:139], off offset:3072 nt
	global_load_dwordx2 v[162:163], v[138:139], off offset:3584 nt
	s_mov_b32 s101, 1
	s_waitcnt vmcnt(0)
	s_branch .Leb_pref
